# baseline (speedup 1.0000x reference)
; #define LAS __attribute__((address_space(3)))
; __device__ __forceinline__ void p0_prologue(const Params& p, LAS unsigned char* lds, int tid) {
;     ...
;     LAS unsigned* scr = (LAS unsigned*)(lds + wave * 8192);
;     const int gw = blockIdx.x * 8 + wave, NGW = gridDim.x * 8;
;     ...
;     for (int it = gw; it < I_LAYER * DEPTH; it += NGW) {
;         const int l = it / I_LAYER; int r = it % I_LAYER;
;         unsigned char* wl = p.ws + (size_t)l * LAYER_BYTES;
.LBB0_427:
	v_readlane_b32 s98, v254, 36
	v_readlane_b32 s99, v253, 34
	s_cmp_gt_u32 s98, 2
	s_cbranch_scc1 .Lmy_w_skip
	s_cmp_lt_u32 s99, 64
	s_cbranch_scc1 .Lmy_w_skip
	v_writelane_b32 v140, s0, 0
	v_writelane_b32 v140, s1, 1
	v_writelane_b32 v140, s2, 2
	v_writelane_b32 v140, s3, 3
	v_writelane_b32 v140, s4, 4
	v_writelane_b32 v140, s5, 5
	v_writelane_b32 v140, s6, 6
	v_writelane_b32 v140, s7, 7
	v_writelane_b32 v140, s8, 8
	v_writelane_b32 v140, s9, 9
	v_writelane_b32 v140, s10, 10
	v_writelane_b32 v140, s11, 11
	v_writelane_b32 v140, s12, 12
	v_writelane_b32 v140, s13, 13
	v_writelane_b32 v140, s14, 14
	v_writelane_b32 v140, s15, 15
	v_writelane_b32 v140, s16, 16
	v_writelane_b32 v140, s17, 17
	v_writelane_b32 v140, s18, 18
	v_writelane_b32 v140, s19, 19
	v_writelane_b32 v140, s20, 20
	v_writelane_b32 v140, s21, 21
	v_writelane_b32 v140, s22, 22
	v_writelane_b32 v140, s23, 23
	v_writelane_b32 v140, s24, 24
	v_writelane_b32 v140, s25, 25
	v_writelane_b32 v140, s26, 26
	v_writelane_b32 v140, s27, 27
	v_writelane_b32 v140, s28, 28
	v_writelane_b32 v140, s29, 29
	v_writelane_b32 v140, s30, 30
	v_writelane_b32 v140, s31, 31
	v_writelane_b32 v140, s32, 32
	v_writelane_b32 v140, s33, 33
	v_writelane_b32 v140, s34, 34
	v_writelane_b32 v140, s35, 35
	v_writelane_b32 v140, s36, 36
	v_writelane_b32 v140, s37, 37
	v_writelane_b32 v140, s38, 38
	v_writelane_b32 v140, s39, 39
	v_writelane_b32 v140, s40, 40
	v_writelane_b32 v140, s41, 41
	v_writelane_b32 v140, s42, 42
	v_writelane_b32 v140, s43, 43
	v_writelane_b32 v140, s44, 44
	v_writelane_b32 v140, s45, 45
	v_writelane_b32 v140, s46, 46
	v_writelane_b32 v140, s47, 47
	v_writelane_b32 v140, s48, 48
	v_writelane_b32 v140, s49, 49
	v_writelane_b32 v140, s50, 50
	v_writelane_b32 v140, s51, 51
	v_writelane_b32 v140, s52, 52
	v_writelane_b32 v140, s53, 53
	v_writelane_b32 v140, s54, 54
	v_writelane_b32 v140, s55, 55
	v_writelane_b32 v140, s56, 56
	v_writelane_b32 v140, s57, 57
	v_writelane_b32 v140, s58, 58
	v_writelane_b32 v140, s59, 59
	v_writelane_b32 v140, s60, 60
	v_writelane_b32 v140, s61, 61
	v_writelane_b32 v140, s62, 62
	v_writelane_b32 v140, s63, 63
	v_writelane_b32 v141, s64, 0
	v_writelane_b32 v141, s65, 1
	v_writelane_b32 v141, s66, 2
	v_writelane_b32 v141, s67, 3
	v_writelane_b32 v141, s68, 4
	v_writelane_b32 v141, s69, 5
	v_writelane_b32 v141, s70, 6
	v_writelane_b32 v141, s71, 7
	v_writelane_b32 v141, s72, 8
	v_writelane_b32 v141, s73, 9
	v_writelane_b32 v141, s74, 10
	v_writelane_b32 v141, s75, 11
	v_writelane_b32 v141, s76, 12
	v_writelane_b32 v141, s77, 13
	v_writelane_b32 v141, s78, 14
	v_writelane_b32 v141, s79, 15
	v_writelane_b32 v141, s80, 16
	v_writelane_b32 v141, s81, 17
	v_writelane_b32 v141, s82, 18
	v_writelane_b32 v141, s83, 19
	v_writelane_b32 v141, s84, 20
	v_writelane_b32 v141, s85, 21
	v_writelane_b32 v141, s86, 22
	v_writelane_b32 v141, s87, 23
	v_writelane_b32 v141, s88, 24
	v_writelane_b32 v141, s89, 25
	v_writelane_b32 v141, s90, 26
	v_writelane_b32 v141, s91, 27
	v_writelane_b32 v141, s92, 28
	v_writelane_b32 v141, s93, 29
	v_writelane_b32 v141, s94, 30
	v_writelane_b32 v141, s95, 31
	v_writelane_b32 v141, s96, 32
	v_writelane_b32 v141, s97, 33
	s_add_i32 s98, s98, 2
	s_mul_i32 s98, s98, 0x2a00
	s_add_i32 s0, s98, 0xffffd600
	s_sub_i32 s1, s99, 64
	s_lshl_b32 s1, s1, 3
	s_add_i32 s0, s0, s1
	v_and_b32_e32 v34, 63, v201
	v_lshrrev_b32_e32 v35, 6, v201
	v_lshlrev_b32_e32 v36, 3, v201
	v_add_u32_e32 v90, s0, v35
	s_add_i32 s99, s98, -1
	s_sub_i32 s10, s94, 64
	s_lshl_b32 s10, s10, 3
	v_readlane_b32 s62, v255, 8
	v_readlane_b32 s63, v255, 9
	s_branch .Lmy_w_entry

; __device__ __forceinline__ u32x4 pack8(f32x4 a, f32x4 b) { u32x4 w; w.x = pk2(a[0], a[1]); w.y = pk2(a[2], a[3]); w.z = pk2(b[0], b[1]); w.w = pk2(b[2], b[3]); return w; }
;     __device__ __forceinline__ void operator()(const f32x4 (&acc)[2][2][4][2], const Unit& un, int wr, int wc, int fr, int fq, int lane) const {
;         const int c0 = un.pn * 128 + wc * 32 + 8 * fq;
;         const f32x4 bv0 = *(const f32x4*)(bias + c0), bv1 = *(const f32x4*)(bias + c0 + 4);
; #pragma unroll
;         for (int ai = 0; ai < 2; ++ai)
; #pragma unroll
;             for (int m = 0; m < 4; ++m) {
;                 const int row = un.pm * 256 + ai * 128 + wr * 64 + m * 16 + fr; float ss = 0.f;
;                 const size_t off = (size_t)row * 1024 + c0, offs = (size_t)row * 2048 + 1024 + c0;
;                 const u32x4 gw = *(const u32x4*)(gb + off);
;                 const f32x4 g0 = (f32x4){bflo(gw.x), bfhi(gw.x), bflo(gw.y), bfhi(gw.y)}, g1 = (f32x4){bflo(gw.z), bfhi(gw.z), bflo(gw.w), bfhi(gw.w)};
;                 const f32x4 z0 = acc[ai][0][m][0] + bv0, z1 = acc[ai][0][m][1] + bv1;
;                 f32x4 o0, o1;
; #pragma unroll
;                 for (int j = 0; j < 4; ++j) { o0[j] = g0[j] * __builtin_amdgcn_rcpf(1.f + __expf(-z0[j])); o1[j] = g1[j] * __builtin_amdgcn_rcpf(1.f + __expf(-z1[j])); ss += o0[j] * o0[j] + o1[j] * o1[j]; }
;                 *(u32x4*)(s + offs) = pack8(o0, o1);
;                 ss += __shfl_xor(ss, 16); ss += __shfl_xor(ss, 32);
;                 if (fq == 0) ssqs[(size_t)row * 32 + un.pn * 4 + wc] = ss;
.LBB0_1062:
	v_lshl_or_b32 v84, s48, 7, v90
	v_ashrrev_i32_e32 v85, 31, v84
	v_lshl_add_u64 v[30:31], v[84:85], 2, s[20:21]
	global_load_dwordx4 v[26:29], v[30:31], off offset:16
	s_nop 0
	global_load_dwordx4 v[30:33], v[30:31], off
	v_lshl_add_u32 v86, s30, 8, v88
	v_ashrrev_i32_e32 v87, 31, v86
	v_lshlrev_b64 v[92:93], 11, v[86:87]
	v_lshl_add_u64 v[92:93], s[0:1], 0, v[92:93]
	v_lshlrev_b64 v[84:85], 1, v[84:85]
	v_lshl_add_u64 v[92:93], v[92:93], 0, v[84:85]
	v_add_co_u32_e32 v128, vcc, 0x8000, v92
	s_nop 1
	v_addc_co_u32_e32 v129, vcc, 0, v93, vcc
	global_load_dwordx4 v[100:103], v[128:129], off
	v_add_co_u32_e32 v128, vcc, 0x8000, v128
	s_nop 1
	v_addc_co_u32_e32 v129, vcc, 0, v129, vcc
	global_load_dwordx4 v[104:107], v[128:129], off
	v_add_co_u32_e32 v128, vcc, 0x8000, v128
	s_nop 1
	v_addc_co_u32_e32 v129, vcc, 0, v129, vcc
	global_load_dwordx4 v[108:111], v[128:129], off
	v_add_co_u32_e32 v128, vcc, 0x28000, v128
	s_nop 1
	v_addc_co_u32_e32 v129, vcc, 0, v129, vcc
	global_load_dwordx4 v[112:115], v[128:129], off
	v_add_co_u32_e32 v128, vcc, 0x8000, v128
	s_nop 1
	v_addc_co_u32_e32 v129, vcc, 0, v129, vcc
	global_load_dwordx4 v[116:119], v[128:129], off
	v_add_co_u32_e32 v128, vcc, 0x8000, v128
	s_nop 1
	v_addc_co_u32_e32 v129, vcc, 0, v129, vcc
	global_load_dwordx4 v[120:123], v[128:129], off
	v_add_co_u32_e32 v128, vcc, 0x8000, v128
	s_nop 1
	v_addc_co_u32_e32 v129, vcc, 0, v129, vcc
	global_load_dwordx4 v[124:127], v[128:129], off
	global_load_dwordx4 v[92:95], v[92:93], off
	s_lshl_b32 s48, s48, 2
	s_ashr_i32 s49, s48, 31
	s_waitcnt vmcnt(0)
	v_add_f32_e32 v66, v66, v26
	v_add_f32_e32 v70, v70, v30
	v_add_f32_e32 v71, v71, v31
	v_add_f32_e32 v67, v67, v27
	v_mul_f32_e32 v70, 0xbfb8aa3b, v70
	v_mul_f32_e32 v66, 0xbfb8aa3b, v66
	v_mul_f32_e32 v71, 0xbfb8aa3b, v71
	v_mul_f32_e32 v67, 0xbfb8aa3b, v67
	v_exp_f32_e32 v70, v70
	v_exp_f32_e32 v66, v66
	v_exp_f32_e32 v71, v71
	v_exp_f32_e32 v67, v67
	v_add_f32_e32 v70, 1.0, v70
	v_add_f32_e32 v66, 1.0, v66
	v_add_f32_e32 v71, 1.0, v71
	v_add_f32_e32 v67, 1.0, v67
	v_rcp_f32_e32 v70, v70
	v_rcp_f32_e32 v66, v66
	v_rcp_f32_e32 v71, v71
	v_rcp_f32_e32 v67, v67
	v_lshlrev_b32_e32 v96, 16, v92
	v_and_b32_e32 v92, 0xffff0000, v92
	v_lshlrev_b32_e32 v98, 16, v94
	v_and_b32_e32 v94, 0xffff0000, v94
	v_mul_f32_e32 v70, v70, v96
	v_mul_f32_e32 v96, v66, v98
	v_mul_f32_e32 v71, v71, v92
	v_mul_f32_e32 v92, v67, v94
	v_mul_f32_e32 v66, v96, v96
	v_mul_f32_e32 v67, v92, v92
	v_fmac_f32_e32 v66, v70, v70
	v_fmac_f32_e32 v67, v71, v71
	v_add_f32_e32 v68, v68, v28
	v_add_f32_e32 v66, v66, v67
	v_add_f32_e32 v67, v72, v32
	v_mul_f32_e32 v68, 0xbfb8aa3b, v68
	v_mul_f32_e32 v67, 0xbfb8aa3b, v67
	v_exp_f32_e32 v68, v68
	v_exp_f32_e32 v67, v67
	v_lshlrev_b32_e32 v99, 16, v95
	v_lshlrev_b32_e32 v97, 16, v93
	v_add_f32_e32 v68, 1.0, v68
	v_add_f32_e32 v67, 1.0, v67
	v_rcp_f32_e32 v68, v68
	v_rcp_f32_e32 v67, v67
	v_add_f32_e32 v69, v69, v29
	v_mul_f32_e32 v69, 0xbfb8aa3b, v69
	v_mul_f32_e32 v72, v68, v99
	v_mul_f32_e32 v67, v67, v97
	v_mul_f32_e32 v68, v72, v72
	v_fmac_f32_e32 v68, v67, v67
	v_add_f32_e32 v66, v68, v66
	v_add_f32_e32 v68, v73, v33
	v_mul_f32_e32 v68, 0xbfb8aa3b, v68
	v_exp_f32_e32 v69, v69
	v_exp_f32_e32 v68, v68
	v_and_b32_e32 v95, 0xffff0000, v95
	v_and_b32_e32 v93, 0xffff0000, v93
	v_add_f32_e32 v69, 1.0, v69
	v_add_f32_e32 v68, 1.0, v68
	v_rcp_f32_e32 v69, v69
	v_rcp_f32_e32 v68, v68
	v_mul_f32_e32 v69, v69, v95
	v_mul_f32_e32 v68, v68, v93
	v_mul_f32_e32 v73, v69, v69
	v_fmac_f32_e32 v73, v68, v68
	v_add_f32_e32 v73, v73, v66
	v_cvt_pk_bf16_f32 v66, v70, v71
	v_lshlrev_b64 v[70:71], 12, v[86:87]
	v_lshl_add_u64 v[70:71], s[22:23], 0, v[70:71]
	v_cvt_pk_bf16_f32 v67, v67, v68
	v_lshl_add_u64 v[70:71], v[70:71], 0, v[84:85]
	v_cvt_pk_bf16_f32 v68, v96, v92
	v_cvt_pk_bf16_f32 v69, v72, v69
	global_store_dwordx4 v[70:71], v[66:69], off offset:2048
	s_nop 1
	v_and_b32_e32 v67, 64, v218
	v_xor_b32_e32 v66, 16, v218
	v_add_u32_e32 v67, 64, v67
	v_cmp_lt_i32_e32 vcc, v66, v67
	v_xor_b32_e32 v69, 32, v218
	s_nop 0
	v_cndmask_b32_e32 v66, v218, v66, vcc
	v_lshlrev_b32_e32 v68, 2, v66
	ds_bpermute_b32 v66, v68, v73
	v_cmp_lt_i32_e32 vcc, v69, v67
	s_waitcnt lgkmcnt(0)
	v_add_f32_e32 v66, v73, v66
	v_cndmask_b32_e32 v67, v218, v69, vcc
	v_lshlrev_b32_e32 v69, 2, v67
	ds_bpermute_b32 v67, v69, v66
	s_and_saveexec_b64 s[30:31], s[36:37]
	s_cbranch_execz .LBB0_1064
	v_lshlrev_b64 v[70:71], 7, v[86:87]
	v_lshl_add_u64 v[70:71], s[24:25], 0, v[70:71]
	v_lshl_add_u64 v[70:71], s[48:49], 2, v[70:71]
	s_lshl_b32 s74, s64, 2
	v_lshl_add_u64 v[70:71], v[70:71], 0, s[74:75]
	s_waitcnt lgkmcnt(0)
	v_add_f32_e32 v66, v66, v67
	global_store_dword v[70:71], v66, off
; __device__ __forceinline__ u32x4 pack8(f32x4 a, f32x4 b) { u32x4 w; w.x = pk2(a[0], a[1]); w.y = pk2(a[2], a[3]); w.z = pk2(b[0], b[1]); w.w = pk2(b[2], b[3]); return w; }
;     __device__ __forceinline__ void operator()(const f32x4 (&acc)[2][2][4][2], const Unit& un, int wr, int wc, int fr, int fq, int lane) const {
;     ...
;                 const int row = un.pm * 256 + ai * 128 + wr * 64 + m * 16 + fr; float ss = 0.f;
;                 const size_t off = (size_t)row * 1024 + c0, offs = (size_t)row * 2048 + 1024 + c0;
;                 const u32x4 gw = *(const u32x4*)(gb + off);
;                 const f32x4 g0 = (f32x4){bflo(gw.x), bfhi(gw.x), bflo(gw.y), bfhi(gw.y)}, g1 = (f32x4){bflo(gw.z), bfhi(gw.z), bflo(gw.w), bfhi(gw.w)};
;                 const f32x4 z0 = acc[ai][0][m][0] + bv0, z1 = acc[ai][0][m][1] + bv1;
;                 f32x4 o0, o1;
; #pragma unroll
;                 for (int j = 0; j < 4; ++j) { o0[j] = g0[j] * __builtin_amdgcn_rcpf(1.f + __expf(-z0[j])); o1[j] = g1[j] * __builtin_amdgcn_rcpf(1.f + __expf(-z1[j])); ss += o0[j] * o0[j] + o1[j] * o1[j]; }
;                 *(u32x4*)(s + offs) = pack8(o0, o1);
;                 ss += __shfl_xor(ss, 16); ss += __shfl_xor(ss, 32);
;                 if (fq == 0) ssqs[(size_t)row * 32 + un.pn * 4 + wc] = ss;
.LBB0_1064:
	s_or_b64 exec, exec, s[30:31]
	v_or_b32_e32 v66, 16, v86
	s_waitcnt lgkmcnt(0)
	v_ashrrev_i32_e32 v67, 31, v66
	v_lshlrev_b64 v[70:71], 11, v[66:67]
	v_lshl_add_u64 v[70:71], s[0:1], 0, v[70:71]
	v_lshl_add_u64 v[70:71], v[70:71], 0, v[84:85]
	v_add_f32_e32 v58, v58, v26
	v_add_f32_e32 v59, v59, v27
	v_add_f32_e32 v62, v62, v30
	v_add_f32_e32 v63, v63, v31
	v_add_f32_e32 v60, v60, v28
	v_add_f32_e32 v65, v65, v33
	v_add_f32_e32 v61, v61, v29
	v_mul_f32_e32 v58, 0xbfb8aa3b, v58
	v_mul_f32_e32 v59, 0xbfb8aa3b, v59
	v_add_f32_e32 v64, v64, v32
	v_mul_f32_e32 v62, 0xbfb8aa3b, v62
	v_mul_f32_e32 v63, 0xbfb8aa3b, v63
	v_mul_f32_e32 v60, 0xbfb8aa3b, v60
	v_mul_f32_e32 v65, 0xbfb8aa3b, v65
	v_mul_f32_e32 v61, 0xbfb8aa3b, v61
	v_exp_f32_e32 v58, v58
	v_exp_f32_e32 v59, v59
	v_mul_f32_e32 v64, 0xbfb8aa3b, v64
	v_exp_f32_e32 v62, v62
	v_exp_f32_e32 v63, v63
	v_exp_f32_e32 v60, v60
	v_exp_f32_e32 v65, v65
	v_exp_f32_e32 v61, v61
	v_exp_f32_e32 v64, v64
	v_add_f32_e32 v58, 1.0, v58
	v_add_f32_e32 v59, 1.0, v59
	v_add_f32_e32 v62, 1.0, v62
	v_add_f32_e32 v63, 1.0, v63
	v_add_f32_e32 v60, 1.0, v60
	v_add_f32_e32 v65, 1.0, v65
	v_add_f32_e32 v61, 1.0, v61
	v_rcp_f32_e32 v58, v58
	v_rcp_f32_e32 v59, v59
	v_add_f32_e32 v64, 1.0, v64
	v_rcp_f32_e32 v62, v62
	v_rcp_f32_e32 v63, v63
	v_rcp_f32_e32 v60, v60
	v_rcp_f32_e32 v65, v65
	v_rcp_f32_e32 v61, v61
	v_rcp_f32_e32 v64, v64
	v_lshlrev_b32_e32 v93, 16, v102
	v_and_b32_e32 v72, 0xffff0000, v102
	v_lshlrev_b32_e32 v87, 16, v100
	v_and_b32_e32 v70, 0xffff0000, v100
	v_lshlrev_b32_e32 v92, 16, v101
	v_and_b32_e32 v71, 0xffff0000, v101
	v_lshlrev_b32_e32 v94, 16, v103
	v_and_b32_e32 v73, 0xffff0000, v103
	v_mul_f32_e32 v58, v58, v93
	v_mul_f32_e32 v59, v59, v72
	v_mul_f32_e32 v62, v62, v87
	v_mul_f32_e32 v63, v63, v70
	v_mul_f32_e32 v70, v60, v94
	v_mul_f32_e32 v65, v65, v71
	v_mul_f32_e32 v71, v61, v73
	v_mul_f32_e32 v60, v58, v58
	v_mul_f32_e32 v61, v59, v59
	v_mul_f32_e32 v64, v64, v92
	v_mul_f32_e32 v72, v70, v70
	v_fmac_f32_e32 v60, v62, v62
	v_fmac_f32_e32 v61, v63, v63
	v_mul_f32_e32 v73, v71, v71
	v_fmac_f32_e32 v72, v64, v64
	v_add_f32_e32 v60, v60, v61
	v_add_f32_e32 v60, v72, v60
	v_fmac_f32_e32 v73, v65, v65
	v_add_f32_e32 v72, v73, v60
	ds_bpermute_b32 v73, v68, v72
	v_cvt_pk_bf16_f32 v60, v62, v63
	v_cvt_pk_bf16_f32 v61, v64, v65
	v_cvt_pk_bf16_f32 v62, v58, v59
	v_lshlrev_b64 v[64:65], 12, v[66:67]
	s_waitcnt lgkmcnt(0)
	v_add_f32_e32 v58, v72, v73
	ds_bpermute_b32 v59, v69, v58
	v_lshl_add_u64 v[64:65], s[22:23], 0, v[64:65]
	v_lshl_add_u64 v[64:65], v[64:65], 0, v[84:85]
	v_cvt_pk_bf16_f32 v63, v70, v71
	global_store_dwordx4 v[64:65], v[60:63], off offset:2048
	s_and_saveexec_b64 s[30:31], s[36:37]
	s_cbranch_execz .LBB0_1066
	v_lshlrev_b64 v[60:61], 7, v[66:67]
	v_lshl_add_u64 v[60:61], s[24:25], 0, v[60:61]
	v_lshl_add_u64 v[60:61], s[48:49], 2, v[60:61]
	s_lshl_b32 s74, s64, 2
	v_lshl_add_u64 v[60:61], v[60:61], 0, s[74:75]
	s_waitcnt lgkmcnt(0)
	v_add_f32_e32 v58, v58, v59
	global_store_dword v[60:61], v58, off
.LBB0_1066:
	s_or_b64 exec, exec, s[30:31]
	v_or_b32_e32 v58, 32, v86
	s_waitcnt lgkmcnt(0)
	v_ashrrev_i32_e32 v59, 31, v58
	v_lshlrev_b64 v[60:61], 11, v[58:59]
	v_lshl_add_u64 v[60:61], s[0:1], 0, v[60:61]
	v_lshl_add_u64 v[60:61], v[60:61], 0, v[84:85]
	v_add_f32_e32 v50, v50, v26
	v_add_f32_e32 v51, v51, v27
	v_add_f32_e32 v54, v54, v30
	v_add_f32_e32 v55, v55, v31
	v_add_f32_e32 v52, v52, v28
	v_add_f32_e32 v57, v57, v33
	v_add_f32_e32 v53, v53, v29
	v_mul_f32_e32 v50, 0xbfb8aa3b, v50
	v_mul_f32_e32 v51, 0xbfb8aa3b, v51
	v_add_f32_e32 v56, v56, v32
	v_mul_f32_e32 v54, 0xbfb8aa3b, v54
	v_mul_f32_e32 v55, 0xbfb8aa3b, v55
	v_mul_f32_e32 v52, 0xbfb8aa3b, v52
	v_mul_f32_e32 v57, 0xbfb8aa3b, v57
	v_mul_f32_e32 v53, 0xbfb8aa3b, v53
	v_exp_f32_e32 v50, v50
	v_exp_f32_e32 v51, v51
	v_mul_f32_e32 v56, 0xbfb8aa3b, v56
	v_exp_f32_e32 v54, v54
	v_exp_f32_e32 v55, v55
	v_exp_f32_e32 v52, v52
	v_exp_f32_e32 v57, v57
	v_exp_f32_e32 v53, v53
	v_exp_f32_e32 v56, v56
	v_add_f32_e32 v50, 1.0, v50
	v_add_f32_e32 v51, 1.0, v51
	v_add_f32_e32 v54, 1.0, v54
	v_add_f32_e32 v55, 1.0, v55
	v_add_f32_e32 v52, 1.0, v52
	v_add_f32_e32 v57, 1.0, v57
	v_add_f32_e32 v53, 1.0, v53
	v_rcp_f32_e32 v50, v50
	v_rcp_f32_e32 v51, v51
	v_add_f32_e32 v56, 1.0, v56
	v_rcp_f32_e32 v54, v54
	v_rcp_f32_e32 v55, v55
	v_rcp_f32_e32 v52, v52
	v_rcp_f32_e32 v57, v57
	v_rcp_f32_e32 v53, v53
	v_rcp_f32_e32 v56, v56
	v_lshlrev_b32_e32 v66, 16, v106
	v_and_b32_e32 v62, 0xffff0000, v106
	v_lshlrev_b32_e32 v64, 16, v104
	v_and_b32_e32 v60, 0xffff0000, v104
	v_lshlrev_b32_e32 v65, 16, v105
	v_and_b32_e32 v61, 0xffff0000, v105
	v_lshlrev_b32_e32 v67, 16, v107
	v_and_b32_e32 v63, 0xffff0000, v107
	v_mul_f32_e32 v50, v50, v66
	v_mul_f32_e32 v51, v51, v62
	v_mul_f32_e32 v54, v54, v64
	v_mul_f32_e32 v55, v55, v60
	v_mul_f32_e32 v60, v52, v67
	v_mul_f32_e32 v57, v57, v61
	v_mul_f32_e32 v61, v53, v63
	v_mul_f32_e32 v52, v50, v50
	v_mul_f32_e32 v53, v51, v51
	v_mul_f32_e32 v56, v56, v65
	v_mul_f32_e32 v62, v60, v60
	v_fmac_f32_e32 v52, v54, v54
	v_fmac_f32_e32 v53, v55, v55
	v_mul_f32_e32 v63, v61, v61
	v_fmac_f32_e32 v62, v56, v56
	v_add_f32_e32 v52, v52, v53
	v_add_f32_e32 v52, v62, v52
	v_fmac_f32_e32 v63, v57, v57
	v_add_f32_e32 v62, v63, v52
	ds_bpermute_b32 v63, v68, v62
	v_cvt_pk_bf16_f32 v52, v54, v55
	v_cvt_pk_bf16_f32 v53, v56, v57
	v_cvt_pk_bf16_f32 v54, v50, v51
	v_lshlrev_b64 v[56:57], 12, v[58:59]
	s_waitcnt lgkmcnt(0)
	v_add_f32_e32 v50, v62, v63
	ds_bpermute_b32 v51, v69, v50
	v_lshl_add_u64 v[56:57], s[22:23], 0, v[56:57]
	v_lshl_add_u64 v[56:57], v[56:57], 0, v[84:85]
	v_cvt_pk_bf16_f32 v55, v60, v61
	global_store_dwordx4 v[56:57], v[52:55], off offset:2048
	s_and_saveexec_b64 s[30:31], s[36:37]
	s_cbranch_execz .LBB0_1068
	v_lshlrev_b64 v[52:53], 7, v[58:59]
	v_lshl_add_u64 v[52:53], s[24:25], 0, v[52:53]
	v_lshl_add_u64 v[52:53], s[48:49], 2, v[52:53]
	s_lshl_b32 s74, s64, 2
	v_lshl_add_u64 v[52:53], v[52:53], 0, s[74:75]
	s_waitcnt lgkmcnt(0)
	v_add_f32_e32 v50, v50, v51
	global_store_dword v[52:53], v50, off
; __device__ __forceinline__ u32x4 pack8(f32x4 a, f32x4 b) { u32x4 w; w.x = pk2(a[0], a[1]); w.y = pk2(a[2], a[3]); w.z = pk2(b[0], b[1]); w.w = pk2(b[2], b[3]); return w; }
;     __device__ __forceinline__ void operator()(const f32x4 (&acc)[2][2][4][2], const Unit& un, int wr, int wc, int fr, int fq, int lane) const {
;     ...
;                 const int row = un.pm * 256 + ai * 128 + wr * 64 + m * 16 + fr; float ss = 0.f;
;                 const size_t off = (size_t)row * 1024 + c0, offs = (size_t)row * 2048 + 1024 + c0;
;                 const u32x4 gw = *(const u32x4*)(gb + off);
;                 const f32x4 g0 = (f32x4){bflo(gw.x), bfhi(gw.x), bflo(gw.y), bfhi(gw.y)}, g1 = (f32x4){bflo(gw.z), bfhi(gw.z), bflo(gw.w), bfhi(gw.w)};
;                 const f32x4 z0 = acc[ai][0][m][0] + bv0, z1 = acc[ai][0][m][1] + bv1;
;                 f32x4 o0, o1;
; #pragma unroll
;                 for (int j = 0; j < 4; ++j) { o0[j] = g0[j] * __builtin_amdgcn_rcpf(1.f + __expf(-z0[j])); o1[j] = g1[j] * __builtin_amdgcn_rcpf(1.f + __expf(-z1[j])); ss += o0[j] * o0[j] + o1[j] * o1[j]; }
;                 *(u32x4*)(s + offs) = pack8(o0, o1);
;                 ss += __shfl_xor(ss, 16); ss += __shfl_xor(ss, 32);
;                 if (fq == 0) ssqs[(size_t)row * 32 + un.pn * 4 + wc] = ss;
.LBB0_1068:
	s_or_b64 exec, exec, s[30:31]
	v_or_b32_e32 v50, 48, v86
	s_waitcnt lgkmcnt(0)
	v_ashrrev_i32_e32 v51, 31, v50
	v_lshlrev_b64 v[52:53], 11, v[50:51]
	v_lshl_add_u64 v[52:53], s[0:1], 0, v[52:53]
	v_lshl_add_u64 v[52:53], v[52:53], 0, v[84:85]
	v_add_f32_e32 v42, v42, v26
	v_add_f32_e32 v43, v43, v27
	v_add_f32_e32 v46, v46, v30
	v_add_f32_e32 v47, v47, v31
	v_add_f32_e32 v44, v44, v28
	v_add_f32_e32 v49, v49, v33
	v_add_f32_e32 v45, v45, v29
	v_mul_f32_e32 v42, 0xbfb8aa3b, v42
	v_mul_f32_e32 v43, 0xbfb8aa3b, v43
	v_add_f32_e32 v48, v48, v32
	v_mul_f32_e32 v46, 0xbfb8aa3b, v46
	v_mul_f32_e32 v47, 0xbfb8aa3b, v47
	v_mul_f32_e32 v44, 0xbfb8aa3b, v44
	v_mul_f32_e32 v49, 0xbfb8aa3b, v49
	v_mul_f32_e32 v45, 0xbfb8aa3b, v45
	v_exp_f32_e32 v42, v42
	v_exp_f32_e32 v43, v43
	v_mul_f32_e32 v48, 0xbfb8aa3b, v48
	v_exp_f32_e32 v46, v46
	v_exp_f32_e32 v47, v47
	v_exp_f32_e32 v44, v44
	v_exp_f32_e32 v49, v49
	v_exp_f32_e32 v45, v45
	v_exp_f32_e32 v48, v48
	v_add_f32_e32 v42, 1.0, v42
	v_add_f32_e32 v43, 1.0, v43
	v_add_f32_e32 v46, 1.0, v46
	v_add_f32_e32 v47, 1.0, v47
	v_add_f32_e32 v44, 1.0, v44
	v_add_f32_e32 v49, 1.0, v49
	v_add_f32_e32 v45, 1.0, v45
	v_rcp_f32_e32 v42, v42
	v_rcp_f32_e32 v43, v43
	v_add_f32_e32 v48, 1.0, v48
	v_rcp_f32_e32 v46, v46
	v_rcp_f32_e32 v47, v47
	v_rcp_f32_e32 v44, v44
	v_rcp_f32_e32 v49, v49
	v_rcp_f32_e32 v45, v45
	v_rcp_f32_e32 v48, v48
	v_lshlrev_b32_e32 v58, 16, v110
	v_and_b32_e32 v54, 0xffff0000, v110
	v_lshlrev_b32_e32 v56, 16, v108
	v_and_b32_e32 v52, 0xffff0000, v108
	v_lshlrev_b32_e32 v57, 16, v109
	v_and_b32_e32 v53, 0xffff0000, v109
	v_lshlrev_b32_e32 v59, 16, v111
	v_and_b32_e32 v55, 0xffff0000, v111
	v_mul_f32_e32 v42, v42, v58
	v_mul_f32_e32 v43, v43, v54
	v_mul_f32_e32 v46, v46, v56
	v_mul_f32_e32 v47, v47, v52
	v_mul_f32_e32 v52, v44, v59
	v_mul_f32_e32 v49, v49, v53
	v_mul_f32_e32 v53, v45, v55
	v_mul_f32_e32 v44, v42, v42
	v_mul_f32_e32 v45, v43, v43
	v_mul_f32_e32 v48, v48, v57
	v_mul_f32_e32 v54, v52, v52
	v_fmac_f32_e32 v44, v46, v46
	v_fmac_f32_e32 v45, v47, v47
	v_mul_f32_e32 v55, v53, v53
	v_fmac_f32_e32 v54, v48, v48
	v_add_f32_e32 v44, v44, v45
	v_add_f32_e32 v44, v54, v44
	v_fmac_f32_e32 v55, v49, v49
	v_add_f32_e32 v54, v55, v44
	ds_bpermute_b32 v55, v68, v54
	v_cvt_pk_bf16_f32 v44, v46, v47
	v_cvt_pk_bf16_f32 v45, v48, v49
	v_cvt_pk_bf16_f32 v46, v42, v43
	v_lshlrev_b64 v[48:49], 12, v[50:51]
	s_waitcnt lgkmcnt(0)
	v_add_f32_e32 v42, v54, v55
	ds_bpermute_b32 v43, v69, v42
	v_lshl_add_u64 v[48:49], s[22:23], 0, v[48:49]
	v_lshl_add_u64 v[48:49], v[48:49], 0, v[84:85]
	v_cvt_pk_bf16_f32 v47, v52, v53
	global_store_dwordx4 v[48:49], v[44:47], off offset:2048
	s_and_saveexec_b64 s[30:31], s[36:37]
	s_cbranch_execz .LBB0_1070
	v_lshlrev_b64 v[44:45], 7, v[50:51]
	v_lshl_add_u64 v[44:45], s[24:25], 0, v[44:45]
	v_lshl_add_u64 v[44:45], s[48:49], 2, v[44:45]
	s_lshl_b32 s74, s64, 2
	v_lshl_add_u64 v[44:45], v[44:45], 0, s[74:75]
	s_waitcnt lgkmcnt(0)
	v_add_f32_e32 v42, v42, v43
	global_store_dword v[44:45], v42, off
.LBB0_1070:
	s_or_b64 exec, exec, s[30:31]
	v_add_u32_e32 v42, 0x80, v86
	s_waitcnt lgkmcnt(0)
	v_ashrrev_i32_e32 v43, 31, v42
	v_lshlrev_b64 v[44:45], 11, v[42:43]
	v_lshl_add_u64 v[44:45], s[0:1], 0, v[44:45]
	v_lshl_add_u64 v[44:45], v[44:45], 0, v[84:85]
	v_add_f32_e32 v34, v34, v26
	v_add_f32_e32 v35, v35, v27
	v_add_f32_e32 v38, v38, v30
	v_add_f32_e32 v39, v39, v31
	v_add_f32_e32 v36, v36, v28
	v_add_f32_e32 v41, v41, v33
	v_add_f32_e32 v37, v37, v29
	v_mul_f32_e32 v34, 0xbfb8aa3b, v34
	v_mul_f32_e32 v35, 0xbfb8aa3b, v35
	v_add_f32_e32 v40, v40, v32
	v_mul_f32_e32 v38, 0xbfb8aa3b, v38
	v_mul_f32_e32 v39, 0xbfb8aa3b, v39
	v_mul_f32_e32 v36, 0xbfb8aa3b, v36
	v_mul_f32_e32 v41, 0xbfb8aa3b, v41
	v_mul_f32_e32 v37, 0xbfb8aa3b, v37
	v_exp_f32_e32 v34, v34
	v_exp_f32_e32 v35, v35
	v_mul_f32_e32 v40, 0xbfb8aa3b, v40
	v_exp_f32_e32 v38, v38
	v_exp_f32_e32 v39, v39
	v_exp_f32_e32 v36, v36
	v_exp_f32_e32 v41, v41
	v_exp_f32_e32 v37, v37
	v_exp_f32_e32 v40, v40
	v_add_f32_e32 v34, 1.0, v34
	v_add_f32_e32 v35, 1.0, v35
	v_add_f32_e32 v38, 1.0, v38
	v_add_f32_e32 v39, 1.0, v39
	v_add_f32_e32 v36, 1.0, v36
	v_add_f32_e32 v41, 1.0, v41
	v_add_f32_e32 v37, 1.0, v37
	v_rcp_f32_e32 v34, v34
	v_rcp_f32_e32 v35, v35
	v_add_f32_e32 v40, 1.0, v40
	v_rcp_f32_e32 v38, v38
	v_rcp_f32_e32 v39, v39
	v_rcp_f32_e32 v36, v36
	v_rcp_f32_e32 v41, v41
	v_rcp_f32_e32 v37, v37
	v_rcp_f32_e32 v40, v40
	v_lshlrev_b32_e32 v50, 16, v114
	v_and_b32_e32 v46, 0xffff0000, v114
	v_lshlrev_b32_e32 v48, 16, v112
	v_and_b32_e32 v44, 0xffff0000, v112
	v_lshlrev_b32_e32 v49, 16, v113
	v_and_b32_e32 v45, 0xffff0000, v113
	v_lshlrev_b32_e32 v51, 16, v115
	v_and_b32_e32 v47, 0xffff0000, v115
	v_mul_f32_e32 v34, v34, v50
	v_mul_f32_e32 v35, v35, v46
	v_mul_f32_e32 v38, v38, v48
	v_mul_f32_e32 v39, v39, v44
	v_mul_f32_e32 v44, v36, v51
	v_mul_f32_e32 v41, v41, v45
	v_mul_f32_e32 v45, v37, v47
	v_mul_f32_e32 v36, v34, v34
	v_mul_f32_e32 v37, v35, v35
	v_mul_f32_e32 v40, v40, v49
	v_mul_f32_e32 v46, v44, v44
	v_fmac_f32_e32 v36, v38, v38
	v_fmac_f32_e32 v37, v39, v39
	v_mul_f32_e32 v47, v45, v45
	v_fmac_f32_e32 v46, v40, v40
	v_add_f32_e32 v36, v36, v37
	v_add_f32_e32 v36, v46, v36
	v_fmac_f32_e32 v47, v41, v41
	v_add_f32_e32 v46, v47, v36
	ds_bpermute_b32 v47, v68, v46
	v_cvt_pk_bf16_f32 v36, v38, v39
	v_cvt_pk_bf16_f32 v37, v40, v41
	v_cvt_pk_bf16_f32 v38, v34, v35
	v_lshlrev_b64 v[40:41], 12, v[42:43]
	s_waitcnt lgkmcnt(0)
	v_add_f32_e32 v34, v46, v47
	ds_bpermute_b32 v35, v69, v34
	v_lshl_add_u64 v[40:41], s[22:23], 0, v[40:41]
	v_lshl_add_u64 v[40:41], v[40:41], 0, v[84:85]
	v_cvt_pk_bf16_f32 v39, v44, v45
	global_store_dwordx4 v[40:41], v[36:39], off offset:2048
	s_and_saveexec_b64 s[30:31], s[36:37]
	s_cbranch_execz .LBB0_1072
	v_lshlrev_b64 v[36:37], 7, v[42:43]
	v_lshl_add_u64 v[36:37], s[24:25], 0, v[36:37]
	v_lshl_add_u64 v[36:37], s[48:49], 2, v[36:37]
	s_lshl_b32 s74, s64, 2
	v_lshl_add_u64 v[36:37], v[36:37], 0, s[74:75]
	s_waitcnt lgkmcnt(0)
	v_add_f32_e32 v34, v34, v35
	global_store_dword v[36:37], v34, off
; __device__ __forceinline__ u32x4 pack8(f32x4 a, f32x4 b) { u32x4 w; w.x = pk2(a[0], a[1]); w.y = pk2(a[2], a[3]); w.z = pk2(b[0], b[1]); w.w = pk2(b[2], b[3]); return w; }
;     __device__ __forceinline__ void operator()(const f32x4 (&acc)[2][2][4][2], const Unit& un, int wr, int wc, int fr, int fq, int lane) const {
;     ...
;                 const int row = un.pm * 256 + ai * 128 + wr * 64 + m * 16 + fr; float ss = 0.f;
;                 const size_t off = (size_t)row * 1024 + c0, offs = (size_t)row * 2048 + 1024 + c0;
;                 const u32x4 gw = *(const u32x4*)(gb + off);
;                 const f32x4 g0 = (f32x4){bflo(gw.x), bfhi(gw.x), bflo(gw.y), bfhi(gw.y)}, g1 = (f32x4){bflo(gw.z), bfhi(gw.z), bflo(gw.w), bfhi(gw.w)};
;                 const f32x4 z0 = acc[ai][0][m][0] + bv0, z1 = acc[ai][0][m][1] + bv1;
;                 f32x4 o0, o1;
; #pragma unroll
;                 for (int j = 0; j < 4; ++j) { o0[j] = g0[j] * __builtin_amdgcn_rcpf(1.f + __expf(-z0[j])); o1[j] = g1[j] * __builtin_amdgcn_rcpf(1.f + __expf(-z1[j])); ss += o0[j] * o0[j] + o1[j] * o1[j]; }
;                 *(u32x4*)(s + offs) = pack8(o0, o1);
;                 ss += __shfl_xor(ss, 16); ss += __shfl_xor(ss, 32);
;                 if (fq == 0) ssqs[(size_t)row * 32 + un.pn * 4 + wc] = ss;
.LBB0_1072:
	s_or_b64 exec, exec, s[30:31]
	v_add_u32_e32 v34, 0x90, v86
	s_waitcnt lgkmcnt(0)
	v_ashrrev_i32_e32 v35, 31, v34
	v_lshlrev_b64 v[36:37], 11, v[34:35]
	v_lshl_add_u64 v[36:37], s[0:1], 0, v[36:37]
	v_lshl_add_u64 v[36:37], v[36:37], 0, v[84:85]
	v_add_f32_e32 v16, v16, v26
	v_add_f32_e32 v17, v17, v27
	v_add_f32_e32 v20, v20, v30
	v_add_f32_e32 v21, v21, v31
	v_add_f32_e32 v18, v18, v28
	v_add_f32_e32 v23, v23, v33
	v_add_f32_e32 v19, v19, v29
	v_mul_f32_e32 v16, 0xbfb8aa3b, v16
	v_mul_f32_e32 v17, 0xbfb8aa3b, v17
	v_add_f32_e32 v22, v22, v32
	v_mul_f32_e32 v20, 0xbfb8aa3b, v20
	v_mul_f32_e32 v21, 0xbfb8aa3b, v21
	v_mul_f32_e32 v18, 0xbfb8aa3b, v18
	v_mul_f32_e32 v23, 0xbfb8aa3b, v23
	v_mul_f32_e32 v19, 0xbfb8aa3b, v19
	v_exp_f32_e32 v16, v16
	v_exp_f32_e32 v17, v17
	v_mul_f32_e32 v22, 0xbfb8aa3b, v22
	v_exp_f32_e32 v20, v20
	v_exp_f32_e32 v21, v21
	v_exp_f32_e32 v18, v18
	v_exp_f32_e32 v23, v23
	v_exp_f32_e32 v19, v19
	v_exp_f32_e32 v22, v22
	v_add_f32_e32 v16, 1.0, v16
	v_add_f32_e32 v17, 1.0, v17
	v_add_f32_e32 v20, 1.0, v20
	v_add_f32_e32 v21, 1.0, v21
	v_add_f32_e32 v18, 1.0, v18
	v_add_f32_e32 v23, 1.0, v23
	v_add_f32_e32 v19, 1.0, v19
	v_rcp_f32_e32 v16, v16
	v_rcp_f32_e32 v17, v17
	v_add_f32_e32 v22, 1.0, v22
	v_rcp_f32_e32 v20, v20
	v_rcp_f32_e32 v21, v21
	v_rcp_f32_e32 v18, v18
	v_rcp_f32_e32 v23, v23
	v_rcp_f32_e32 v19, v19
	v_rcp_f32_e32 v22, v22
	v_lshlrev_b32_e32 v42, 16, v118
	v_and_b32_e32 v38, 0xffff0000, v118
	v_lshlrev_b32_e32 v40, 16, v116
	v_and_b32_e32 v36, 0xffff0000, v116
	v_lshlrev_b32_e32 v41, 16, v117
	v_and_b32_e32 v37, 0xffff0000, v117
	v_lshlrev_b32_e32 v43, 16, v119
	v_and_b32_e32 v39, 0xffff0000, v119
	v_mul_f32_e32 v16, v16, v42
	v_mul_f32_e32 v17, v17, v38
	v_mul_f32_e32 v20, v20, v40
	v_mul_f32_e32 v21, v21, v36
	v_mul_f32_e32 v36, v18, v43
	v_mul_f32_e32 v23, v23, v37
	v_mul_f32_e32 v37, v19, v39
	v_mul_f32_e32 v18, v16, v16
	v_mul_f32_e32 v19, v17, v17
	v_mul_f32_e32 v22, v22, v41
	v_mul_f32_e32 v38, v36, v36
	v_fmac_f32_e32 v18, v20, v20
	v_fmac_f32_e32 v19, v21, v21
	v_mul_f32_e32 v39, v37, v37
	v_fmac_f32_e32 v38, v22, v22
	v_add_f32_e32 v18, v18, v19
	v_add_f32_e32 v18, v38, v18
	v_fmac_f32_e32 v39, v23, v23
	v_add_f32_e32 v38, v39, v18
	ds_bpermute_b32 v39, v68, v38
	v_cvt_pk_bf16_f32 v18, v20, v21
	v_cvt_pk_bf16_f32 v19, v22, v23
	v_cvt_pk_bf16_f32 v20, v16, v17
	v_lshlrev_b64 v[22:23], 12, v[34:35]
	s_waitcnt lgkmcnt(0)
	v_add_f32_e32 v16, v38, v39
	ds_bpermute_b32 v17, v69, v16
	v_lshl_add_u64 v[22:23], s[22:23], 0, v[22:23]
	v_lshl_add_u64 v[22:23], v[22:23], 0, v[84:85]
	v_cvt_pk_bf16_f32 v21, v36, v37
	global_store_dwordx4 v[22:23], v[18:21], off offset:2048
	s_and_saveexec_b64 s[30:31], s[36:37]
	s_cbranch_execz .LBB0_1074
	v_lshlrev_b64 v[18:19], 7, v[34:35]
	v_lshl_add_u64 v[18:19], s[24:25], 0, v[18:19]
	v_lshl_add_u64 v[18:19], s[48:49], 2, v[18:19]
	s_lshl_b32 s74, s64, 2
	v_lshl_add_u64 v[18:19], v[18:19], 0, s[74:75]
	s_waitcnt lgkmcnt(0)
	v_add_f32_e32 v16, v16, v17
	global_store_dword v[18:19], v16, off
; __device__ __forceinline__ u32x4 pack8(f32x4 a, f32x4 b) { u32x4 w; w.x = pk2(a[0], a[1]); w.y = pk2(a[2], a[3]); w.z = pk2(b[0], b[1]); w.w = pk2(b[2], b[3]); return w; }
;     __device__ __forceinline__ void operator()(const f32x4 (&acc)[2][2][4][2], const Unit& un, int wr, int wc, int fr, int fq, int lane) const {
;     ...
;                 const int row = un.pm * 256 + ai * 128 + wr * 64 + m * 16 + fr; float ss = 0.f;
;                 const size_t off = (size_t)row * 1024 + c0, offs = (size_t)row * 2048 + 1024 + c0;
;                 const u32x4 gw = *(const u32x4*)(gb + off);
;                 const f32x4 g0 = (f32x4){bflo(gw.x), bfhi(gw.x), bflo(gw.y), bfhi(gw.y)}, g1 = (f32x4){bflo(gw.z), bfhi(gw.z), bflo(gw.w), bfhi(gw.w)};
;                 const f32x4 z0 = acc[ai][0][m][0] + bv0, z1 = acc[ai][0][m][1] + bv1;
;                 f32x4 o0, o1;
; #pragma unroll
;                 for (int j = 0; j < 4; ++j) { o0[j] = g0[j] * __builtin_amdgcn_rcpf(1.f + __expf(-z0[j])); o1[j] = g1[j] * __builtin_amdgcn_rcpf(1.f + __expf(-z1[j])); ss += o0[j] * o0[j] + o1[j] * o1[j]; }
;                 *(u32x4*)(s + offs) = pack8(o0, o1);
;                 ss += __shfl_xor(ss, 16); ss += __shfl_xor(ss, 32);
;                 if (fq == 0) ssqs[(size_t)row * 32 + un.pn * 4 + wc] = ss;
.LBB0_1074:
	s_or_b64 exec, exec, s[30:31]
	v_add_u32_e32 v16, 0xa0, v86
	s_waitcnt lgkmcnt(0)
	v_ashrrev_i32_e32 v17, 31, v16
	v_lshlrev_b64 v[18:19], 11, v[16:17]
	v_lshl_add_u64 v[18:19], s[0:1], 0, v[18:19]
	v_lshl_add_u64 v[18:19], v[18:19], 0, v[84:85]
	v_add_f32_e32 v8, v8, v26
	v_add_f32_e32 v9, v9, v27
	v_add_f32_e32 v12, v12, v30
	v_add_f32_e32 v13, v13, v31
	v_add_f32_e32 v10, v10, v28
	v_add_f32_e32 v15, v15, v33
	v_add_f32_e32 v11, v11, v29
	v_mul_f32_e32 v8, 0xbfb8aa3b, v8
	v_mul_f32_e32 v9, 0xbfb8aa3b, v9
	v_add_f32_e32 v14, v14, v32
	v_mul_f32_e32 v12, 0xbfb8aa3b, v12
	v_mul_f32_e32 v13, 0xbfb8aa3b, v13
	v_mul_f32_e32 v10, 0xbfb8aa3b, v10
	v_mul_f32_e32 v15, 0xbfb8aa3b, v15
	v_mul_f32_e32 v11, 0xbfb8aa3b, v11
	v_exp_f32_e32 v8, v8
	v_exp_f32_e32 v9, v9
	v_mul_f32_e32 v14, 0xbfb8aa3b, v14
	v_exp_f32_e32 v12, v12
	v_exp_f32_e32 v13, v13
	v_exp_f32_e32 v10, v10
	v_exp_f32_e32 v15, v15
	v_exp_f32_e32 v11, v11
	v_exp_f32_e32 v14, v14
	v_add_f32_e32 v8, 1.0, v8
	v_add_f32_e32 v9, 1.0, v9
	v_add_f32_e32 v12, 1.0, v12
	v_add_f32_e32 v13, 1.0, v13
	v_add_f32_e32 v10, 1.0, v10
	v_add_f32_e32 v15, 1.0, v15
	v_add_f32_e32 v11, 1.0, v11
	v_rcp_f32_e32 v8, v8
	v_rcp_f32_e32 v9, v9
	v_add_f32_e32 v14, 1.0, v14
	v_rcp_f32_e32 v12, v12
	v_rcp_f32_e32 v13, v13
	v_rcp_f32_e32 v10, v10
	v_rcp_f32_e32 v15, v15
	v_rcp_f32_e32 v11, v11
	v_rcp_f32_e32 v14, v14
	v_lshlrev_b32_e32 v34, 16, v122
	v_and_b32_e32 v20, 0xffff0000, v122
	v_lshlrev_b32_e32 v22, 16, v120
	v_and_b32_e32 v18, 0xffff0000, v120
	v_lshlrev_b32_e32 v23, 16, v121
	v_and_b32_e32 v19, 0xffff0000, v121
	v_lshlrev_b32_e32 v35, 16, v123
	v_and_b32_e32 v21, 0xffff0000, v123
	v_mul_f32_e32 v8, v8, v34
	v_mul_f32_e32 v9, v9, v20
	v_mul_f32_e32 v12, v12, v22
	v_mul_f32_e32 v13, v13, v18
	v_mul_f32_e32 v18, v10, v35
	v_mul_f32_e32 v15, v15, v19
	v_mul_f32_e32 v19, v11, v21
	v_mul_f32_e32 v10, v8, v8
	v_mul_f32_e32 v11, v9, v9
	v_mul_f32_e32 v14, v14, v23
	v_mul_f32_e32 v20, v18, v18
	v_fmac_f32_e32 v10, v12, v12
	v_fmac_f32_e32 v11, v13, v13
	v_mul_f32_e32 v21, v19, v19
	v_fmac_f32_e32 v20, v14, v14
	v_add_f32_e32 v10, v10, v11
	v_add_f32_e32 v10, v20, v10
	v_fmac_f32_e32 v21, v15, v15
	v_add_f32_e32 v20, v21, v10
	ds_bpermute_b32 v21, v68, v20
	v_cvt_pk_bf16_f32 v10, v12, v13
	v_cvt_pk_bf16_f32 v11, v14, v15
	v_cvt_pk_bf16_f32 v12, v8, v9
	v_lshlrev_b64 v[14:15], 12, v[16:17]
	s_waitcnt lgkmcnt(0)
	v_add_f32_e32 v8, v20, v21
	ds_bpermute_b32 v9, v69, v8
	v_lshl_add_u64 v[14:15], s[22:23], 0, v[14:15]
	v_lshl_add_u64 v[14:15], v[14:15], 0, v[84:85]
	v_cvt_pk_bf16_f32 v13, v18, v19
	global_store_dwordx4 v[14:15], v[10:13], off offset:2048
	s_and_saveexec_b64 s[30:31], s[36:37]
	s_cbranch_execz .LBB0_1076
	v_lshlrev_b64 v[10:11], 7, v[16:17]
	v_lshl_add_u64 v[10:11], s[24:25], 0, v[10:11]
	v_lshl_add_u64 v[10:11], s[48:49], 2, v[10:11]
	s_lshl_b32 s74, s64, 2
	v_lshl_add_u64 v[10:11], v[10:11], 0, s[74:75]
	s_waitcnt lgkmcnt(0)
	v_add_f32_e32 v8, v8, v9
	global_store_dword v[10:11], v8, off
.LBB0_1076:
	s_or_b64 exec, exec, s[30:31]
	v_add_u32_e32 v8, 0xb0, v86
	s_waitcnt lgkmcnt(0)
	v_ashrrev_i32_e32 v9, 31, v8
	v_lshlrev_b64 v[10:11], 11, v[8:9]
	v_lshl_add_u64 v[10:11], s[0:1], 0, v[10:11]
	v_lshl_add_u64 v[10:11], v[10:11], 0, v[84:85]
	v_add_f32_e32 v0, v0, v26
	v_add_f32_e32 v1, v1, v27
	v_add_f32_e32 v4, v4, v30
	v_add_f32_e32 v5, v5, v31
	v_add_f32_e32 v2, v2, v28
	v_add_f32_e32 v7, v7, v33
	v_add_f32_e32 v3, v3, v29
	v_mul_f32_e32 v0, 0xbfb8aa3b, v0
	v_mul_f32_e32 v1, 0xbfb8aa3b, v1
	v_add_f32_e32 v6, v6, v32
	v_mul_f32_e32 v4, 0xbfb8aa3b, v4
	v_mul_f32_e32 v5, 0xbfb8aa3b, v5
	v_mul_f32_e32 v2, 0xbfb8aa3b, v2
	v_mul_f32_e32 v7, 0xbfb8aa3b, v7
	v_mul_f32_e32 v3, 0xbfb8aa3b, v3
	v_exp_f32_e32 v0, v0
	v_exp_f32_e32 v1, v1
	v_mul_f32_e32 v6, 0xbfb8aa3b, v6
	v_exp_f32_e32 v4, v4
	v_exp_f32_e32 v5, v5
	v_exp_f32_e32 v2, v2
	v_exp_f32_e32 v7, v7
	v_exp_f32_e32 v3, v3
	v_exp_f32_e32 v6, v6
	v_add_f32_e32 v0, 1.0, v0
	v_add_f32_e32 v1, 1.0, v1
	v_add_f32_e32 v4, 1.0, v4
	v_add_f32_e32 v5, 1.0, v5
	v_add_f32_e32 v2, 1.0, v2
	v_add_f32_e32 v7, 1.0, v7
	v_add_f32_e32 v3, 1.0, v3
	v_rcp_f32_e32 v0, v0
	v_rcp_f32_e32 v1, v1
	v_add_f32_e32 v6, 1.0, v6
	v_rcp_f32_e32 v4, v4
	v_rcp_f32_e32 v5, v5
	v_rcp_f32_e32 v2, v2
	v_rcp_f32_e32 v7, v7
	v_rcp_f32_e32 v3, v3
	v_rcp_f32_e32 v6, v6
	v_lshlrev_b32_e32 v16, 16, v126
	v_and_b32_e32 v12, 0xffff0000, v126
	v_lshlrev_b32_e32 v14, 16, v124
	v_and_b32_e32 v10, 0xffff0000, v124
	v_lshlrev_b32_e32 v15, 16, v125
	v_and_b32_e32 v11, 0xffff0000, v125
	v_lshlrev_b32_e32 v17, 16, v127
	v_and_b32_e32 v13, 0xffff0000, v127
	v_mul_f32_e32 v0, v0, v16
	v_mul_f32_e32 v1, v1, v12
	v_mul_f32_e32 v4, v4, v14
	v_mul_f32_e32 v5, v5, v10
	v_mul_f32_e32 v10, v2, v17
	v_mul_f32_e32 v7, v7, v11
	v_mul_f32_e32 v11, v3, v13
	v_mul_f32_e32 v2, v0, v0
	v_mul_f32_e32 v3, v1, v1
	v_mul_f32_e32 v6, v6, v15
	v_mul_f32_e32 v12, v10, v10
	v_fmac_f32_e32 v2, v4, v4
	v_fmac_f32_e32 v3, v5, v5
	v_mul_f32_e32 v13, v11, v11
	v_fmac_f32_e32 v12, v6, v6
	v_add_f32_e32 v2, v2, v3
	v_add_f32_e32 v2, v12, v2
	v_fmac_f32_e32 v13, v7, v7
	v_add_f32_e32 v12, v13, v2
	ds_bpermute_b32 v13, v68, v12
	v_cvt_pk_bf16_f32 v2, v4, v5
	v_cvt_pk_bf16_f32 v3, v6, v7
	v_cvt_pk_bf16_f32 v4, v0, v1
	v_lshlrev_b64 v[6:7], 12, v[8:9]
	s_waitcnt lgkmcnt(0)
	v_add_f32_e32 v0, v12, v13
	ds_bpermute_b32 v1, v69, v0
	v_lshl_add_u64 v[6:7], s[22:23], 0, v[6:7]
	v_lshl_add_u64 v[6:7], v[6:7], 0, v[84:85]
	v_cvt_pk_bf16_f32 v5, v10, v11
	global_store_dwordx4 v[6:7], v[2:5], off offset:2048
	s_and_saveexec_b64 s[30:31], s[36:37]
	s_cbranch_execz .LBB0_1078
	v_lshlrev_b64 v[2:3], 7, v[8:9]
	v_lshl_add_u64 v[2:3], s[24:25], 0, v[2:3]
	v_lshl_add_u64 v[2:3], s[48:49], 2, v[2:3]
	s_lshl_b32 s74, s64, 2
	v_lshl_add_u64 v[2:3], v[2:3], 0, s[74:75]
	s_waitcnt lgkmcnt(0)
	v_add_f32_e32 v0, v0, v1
	global_store_dword v[2:3], v0, off
